# baseline (speedup 1.0000x reference)
; #define MFMA(a, b, c) __builtin_amdgcn_mfma_f32_16x16x32_bf16((a), (b), (c), 0, 0, 0)
; __device__ __forceinline__ void mla_attn_job(const Params& p, int half, int job, char* smem) {
;     ...
; #pragma unroll
;     for (int t = 0; t < QT; ++t) {
;       float ps = 0.f;
;       const float mr = mrun[t];
; #pragma unroll
;       for (int mt = 0; mt < 4; ++mt)
; #pragma unroll
;         for (int j = 0; j < 4; ++j) {
;           float e = __builtin_amdgcn_exp2f(sc[mt][t][j] - mr);
;           sc[mt][t][j] = e;
;           ps += e;
;         }
;       lrun[t] += ps;
; #pragma unroll
;       for (int tl = 0; tl < 2; ++tl) {
;         unsigned w0 = pack2(sc[2 * tl][t][0], sc[2 * tl][t][1]), w1 = pack2(sc[2 * tl][t][2], sc[2 * tl][t][3]);
;         unsigned w2 = pack2(sc[2 * tl + 1][t][0], sc[2 * tl + 1][t][1]), w3 = pack2(sc[2 * tl + 1][t][2], sc[2 * tl + 1][t][3]);
;         bf16x8 a;
;         a[0] = (short)(w0 & 0xffff); a[1] = (short)(w0 >> 16); a[2] = (short)(w1 & 0xffff); a[3] = (short)(w1 >> 16);
;         a[4] = (short)(w2 & 0xffff); a[5] = (short)(w2 >> 16); a[6] = (short)(w3 & 0xffff); a[7] = (short)(w3 >> 16);
;         pa[t][tl] = a;
;       }
;     }
;     __builtin_amdgcn_s_setprio(1);
; #pragma unroll
;     for (int tl = 0; tl < 2; ++tl)
; #pragma unroll
;       for (int n = 0; n < 4; ++n) {
;         bf16x8 b = *(const bf16x8*)(Vt + (n * 16 + fr) * 72 + tl * 32 + fq * 8);
; #pragma unroll
;         for (int t = 0; t < QT; ++t) oacc[t][n] = MFMA(pa[t][tl], b, oacc[t][n]);
;       }
;     __builtin_amdgcn_s_setprio(0);
.LBB0_222:
	s_setprio 1
	v_add3_u32 v224, s26, v233, v232
	ds_read_b128 v[238:241], v224 offset:13312
	ds_read_b128 v[242:245], v224 offset:15616
	ds_read_b128 v[246:249], v224 offset:17920
	ds_read_b128 v[250:253], v224 offset:20224
	v_sub_f32_e32 v160, v160, v237
	v_sub_f32_e32 v161, v161, v237
	v_sub_f32_e32 v162, v162, v237
	v_sub_f32_e32 v163, v163, v237
	v_exp_f32_e32 v160, v160
	v_exp_f32_e32 v161, v161
	v_exp_f32_e32 v162, v162
	v_exp_f32_e32 v163, v163
	v_add_f32_e32 v228, v160, v161
	v_add_f32_e32 v228, v228, v162
	v_add_f32_e32 v228, v228, v163
	v_sub_f32_e32 v180, v180, v237
	v_sub_f32_e32 v181, v181, v237
	v_sub_f32_e32 v182, v182, v237
	v_sub_f32_e32 v183, v183, v237
	v_exp_f32_e32 v180, v180
	v_exp_f32_e32 v181, v181
	v_exp_f32_e32 v182, v182
	v_exp_f32_e32 v183, v183
	v_add_f32_e32 v228, v228, v180
	v_add_f32_e32 v228, v228, v181
	v_add_f32_e32 v228, v228, v182
	v_add_f32_e32 v228, v228, v183
	v_cvt_pk_bf16_f32 v160, v160, v161
	v_cvt_pk_bf16_f32 v161, v162, v163
	v_cvt_pk_bf16_f32 v162, v180, v181
	v_cvt_pk_bf16_f32 v163, v182, v183
	s_waitcnt lgkmcnt(0)
	s_nop 1
	v_mfma_f32_16x16x32_bf16 v[96:99], v[160:163], v[238:241], v[96:99]
	v_sub_f32_e32 v156, v156, v236
	v_sub_f32_e32 v157, v157, v236
	v_sub_f32_e32 v158, v158, v236
	v_sub_f32_e32 v159, v159, v236
	v_exp_f32_e32 v156, v156
	v_exp_f32_e32 v157, v157
	v_exp_f32_e32 v158, v158
	v_mfma_f32_16x16x32_bf16 v[100:103], v[160:163], v[242:245], v[100:103]
	v_exp_f32_e32 v159, v159
	v_add_f32_e32 v229, v156, v157
	v_add_f32_e32 v229, v229, v158
	v_add_f32_e32 v229, v229, v159
	v_sub_f32_e32 v168, v168, v236
	v_sub_f32_e32 v169, v169, v236
	v_sub_f32_e32 v170, v170, v236
	v_mfma_f32_16x16x32_bf16 v[104:107], v[160:163], v[246:249], v[104:107]
	v_sub_f32_e32 v171, v171, v236
	v_exp_f32_e32 v168, v168
	v_exp_f32_e32 v169, v169
	v_exp_f32_e32 v170, v170
	v_exp_f32_e32 v171, v171
	v_add_f32_e32 v229, v229, v168
	v_add_f32_e32 v229, v229, v169
	v_mfma_f32_16x16x32_bf16 v[108:111], v[160:163], v[250:253], v[108:111]
	v_add_f32_e32 v229, v229, v170
	v_add_f32_e32 v229, v229, v171
	v_cvt_pk_bf16_f32 v156, v156, v157
	v_cvt_pk_bf16_f32 v157, v158, v159
	v_cvt_pk_bf16_f32 v158, v168, v169
	v_cvt_pk_bf16_f32 v159, v170, v171
	ds_read_b128 v[168:171], v224 offset:13376
	s_nop 1
	v_mfma_f32_16x16x32_bf16 v[32:35], v[156:159], v[238:241], v[32:35]
	v_sub_f32_e32 v136, v136, v235
	v_sub_f32_e32 v137, v137, v235
	v_sub_f32_e32 v138, v138, v235
	v_sub_f32_e32 v139, v139, v235
	v_exp_f32_e32 v136, v136
	v_exp_f32_e32 v137, v137
	v_exp_f32_e32 v138, v138
	v_mfma_f32_16x16x32_bf16 v[36:39], v[156:159], v[242:245], v[36:39]
	v_exp_f32_e32 v139, v139
	v_add_f32_e32 v230, v136, v137
	v_add_f32_e32 v230, v230, v138
	v_add_f32_e32 v230, v230, v139
	v_sub_f32_e32 v148, v148, v235
	v_sub_f32_e32 v149, v149, v235
	v_sub_f32_e32 v150, v150, v235
	v_mfma_f32_16x16x32_bf16 v[40:43], v[156:159], v[246:249], v[40:43]
	v_sub_f32_e32 v151, v151, v235
	v_exp_f32_e32 v148, v148
	v_exp_f32_e32 v149, v149
	v_exp_f32_e32 v150, v150
	v_exp_f32_e32 v151, v151
	v_add_f32_e32 v230, v230, v148
	v_add_f32_e32 v230, v230, v149
	v_mfma_f32_16x16x32_bf16 v[44:47], v[156:159], v[250:253], v[44:47]
	v_add_f32_e32 v230, v230, v150
	v_add_f32_e32 v230, v230, v151
	v_cvt_pk_bf16_f32 v136, v136, v137
	v_cvt_pk_bf16_f32 v137, v138, v139
	v_cvt_pk_bf16_f32 v138, v148, v149
	v_cvt_pk_bf16_f32 v139, v150, v151
	ds_read_b128 v[148:151], v224 offset:15680
	s_nop 1
	v_mfma_f32_16x16x32_bf16 v[16:19], v[136:139], v[238:241], v[16:19]
	v_sub_f32_e32 v132, v132, v234
	v_sub_f32_e32 v133, v133, v234
	v_sub_f32_e32 v134, v134, v234
	v_sub_f32_e32 v135, v135, v234
	v_exp_f32_e32 v132, v132
	v_exp_f32_e32 v133, v133
	v_exp_f32_e32 v134, v134
	v_mfma_f32_16x16x32_bf16 v[20:23], v[136:139], v[242:245], v[20:23]
	v_exp_f32_e32 v135, v135
	v_add_f32_e32 v180, v132, v133
	v_add_f32_e32 v180, v180, v134
	v_add_f32_e32 v180, v180, v135
	v_sub_f32_e32 v140, v140, v234
	v_sub_f32_e32 v141, v141, v234
	v_sub_f32_e32 v142, v142, v234
	v_mfma_f32_16x16x32_bf16 v[24:27], v[136:139], v[246:249], v[24:27]
	v_sub_f32_e32 v143, v143, v234
	v_exp_f32_e32 v140, v140
	v_exp_f32_e32 v141, v141
	v_exp_f32_e32 v142, v142
	v_exp_f32_e32 v143, v143
	v_add_f32_e32 v180, v180, v140
	v_add_f32_e32 v180, v180, v141
	v_mfma_f32_16x16x32_bf16 v[28:31], v[136:139], v[250:253], v[28:31]
	v_add_f32_e32 v180, v180, v142
	v_add_f32_e32 v180, v180, v143
	v_cvt_pk_bf16_f32 v132, v132, v133
	v_cvt_pk_bf16_f32 v133, v134, v135
	v_cvt_pk_bf16_f32 v134, v140, v141
	v_cvt_pk_bf16_f32 v135, v142, v143
	ds_read_b128 v[140:143], v224 offset:17984
	s_nop 1
	v_mfma_f32_16x16x32_bf16 v[0:3], v[132:135], v[238:241], v[0:3]
	ds_read_b128 v[238:241], v224 offset:20288
	v_sub_f32_e32 v184, v184, v237
	v_sub_f32_e32 v185, v185, v237
	v_sub_f32_e32 v186, v186, v237
	v_sub_f32_e32 v187, v187, v237
	v_exp_f32_e32 v184, v184
	v_exp_f32_e32 v185, v185
	v_exp_f32_e32 v186, v186
	v_exp_f32_e32 v187, v187
	v_mfma_f32_16x16x32_bf16 v[4:7], v[132:135], v[242:245], v[4:7]
	v_add_f32_e32 v228, v228, v184
	v_add_f32_e32 v228, v228, v185
	v_add_f32_e32 v228, v228, v186
	v_add_f32_e32 v228, v228, v187
	v_sub_f32_e32 v192, v192, v237
	v_sub_f32_e32 v193, v193, v237
	v_sub_f32_e32 v194, v194, v237
	v_sub_f32_e32 v195, v195, v237
	v_mfma_f32_16x16x32_bf16 v[8:11], v[132:135], v[246:249], v[8:11]
	v_exp_f32_e32 v192, v192
	v_exp_f32_e32 v193, v193
	v_exp_f32_e32 v194, v194
	v_exp_f32_e32 v195, v195
	v_add_f32_e32 v228, v228, v192
	v_add_f32_e32 v228, v228, v193
	v_add_f32_e32 v228, v228, v194
	v_add_f32_e32 v228, v228, v195
	v_mfma_f32_16x16x32_bf16 v[12:15], v[132:135], v[250:253], v[12:15]
	v_add_f32_e32 v205, v205, v228
	v_cvt_pk_bf16_f32 v184, v184, v185
	v_cvt_pk_bf16_f32 v185, v186, v187
	v_cvt_pk_bf16_f32 v186, v192, v193
	v_cvt_pk_bf16_f32 v187, v194, v195
	s_waitcnt lgkmcnt(0)
; #define MFMA(a, b, c) __builtin_amdgcn_mfma_f32_16x16x32_bf16((a), (b), (c), 0, 0, 0)
; __device__ __forceinline__ void mla_attn_job(const Params& p, int half, int job, char* smem) {
;     ...
; #pragma unroll
;     for (int t = 0; t < QT; ++t) {
;       float ps = 0.f;
;       const float mr = mrun[t];
; #pragma unroll
;       for (int mt = 0; mt < 4; ++mt)
; #pragma unroll
;         for (int j = 0; j < 4; ++j) {
;           float e = __builtin_amdgcn_exp2f(sc[mt][t][j] - mr);
;           sc[mt][t][j] = e;
;           ps += e;
;         }
;       lrun[t] += ps;
; #pragma unroll
;       for (int tl = 0; tl < 2; ++tl) {
;         unsigned w0 = pack2(sc[2 * tl][t][0], sc[2 * tl][t][1]), w1 = pack2(sc[2 * tl][t][2], sc[2 * tl][t][3]);
;         unsigned w2 = pack2(sc[2 * tl + 1][t][0], sc[2 * tl + 1][t][1]), w3 = pack2(sc[2 * tl + 1][t][2], sc[2 * tl + 1][t][3]);
;         bf16x8 a;
;         a[0] = (short)(w0 & 0xffff); a[1] = (short)(w0 >> 16); a[2] = (short)(w1 & 0xffff); a[3] = (short)(w1 >> 16);
;         a[4] = (short)(w2 & 0xffff); a[5] = (short)(w2 >> 16); a[6] = (short)(w3 & 0xffff); a[7] = (short)(w3 >> 16);
;         pa[t][tl] = a;
;       }
;     }
;     __builtin_amdgcn_s_setprio(1);
; #pragma unroll
;     for (int tl = 0; tl < 2; ++tl)
; #pragma unroll
;       for (int n = 0; n < 4; ++n) {
;         bf16x8 b = *(const bf16x8*)(Vt + (n * 16 + fr) * 72 + tl * 32 + fq * 8);
; #pragma unroll
;         for (int t = 0; t < QT; ++t) oacc[t][n] = MFMA(pa[t][tl], b, oacc[t][n]);
;       }
;     __builtin_amdgcn_s_setprio(0);
;   }
	s_nop 1
	v_mfma_f32_16x16x32_bf16 v[96:99], v[184:187], v[168:171], v[96:99]
	v_sub_f32_e32 v172, v172, v236
	v_sub_f32_e32 v173, v173, v236
	v_sub_f32_e32 v174, v174, v236
	v_sub_f32_e32 v175, v175, v236
	v_exp_f32_e32 v172, v172
	v_exp_f32_e32 v173, v173
	v_exp_f32_e32 v174, v174
	v_exp_f32_e32 v175, v175
	v_mfma_f32_16x16x32_bf16 v[100:103], v[184:187], v[148:151], v[100:103]
	v_add_f32_e32 v229, v229, v172
	v_add_f32_e32 v229, v229, v173
	v_add_f32_e32 v229, v229, v174
	v_add_f32_e32 v229, v229, v175
	v_sub_f32_e32 v188, v188, v236
	v_sub_f32_e32 v189, v189, v236
	v_sub_f32_e32 v190, v190, v236
	v_sub_f32_e32 v191, v191, v236
	v_mfma_f32_16x16x32_bf16 v[104:107], v[184:187], v[140:143], v[104:107]
	v_exp_f32_e32 v188, v188
	v_exp_f32_e32 v189, v189
	v_exp_f32_e32 v190, v190
	v_exp_f32_e32 v191, v191
	v_add_f32_e32 v229, v229, v188
	v_add_f32_e32 v229, v229, v189
	v_add_f32_e32 v229, v229, v190
	v_add_f32_e32 v229, v229, v191
	v_mfma_f32_16x16x32_bf16 v[108:111], v[184:187], v[238:241], v[108:111]
	v_add_f32_e32 v204, v204, v229
	v_cvt_pk_bf16_f32 v172, v172, v173
	v_cvt_pk_bf16_f32 v173, v174, v175
	v_cvt_pk_bf16_f32 v174, v188, v189
	v_cvt_pk_bf16_f32 v175, v190, v191
	s_nop 1
	v_mfma_f32_16x16x32_bf16 v[32:35], v[172:175], v[168:171], v[32:35]
	v_sub_f32_e32 v152, v152, v235
	v_sub_f32_e32 v153, v153, v235
	v_sub_f32_e32 v154, v154, v235
	v_sub_f32_e32 v155, v155, v235
	v_exp_f32_e32 v152, v152
	v_exp_f32_e32 v153, v153
	v_exp_f32_e32 v154, v154
	v_exp_f32_e32 v155, v155
	v_mfma_f32_16x16x32_bf16 v[36:39], v[172:175], v[148:151], v[36:39]
	v_add_f32_e32 v230, v230, v152
	v_add_f32_e32 v230, v230, v153
	v_add_f32_e32 v230, v230, v154
	v_add_f32_e32 v230, v230, v155
	v_sub_f32_e32 v176, v176, v235
	v_sub_f32_e32 v177, v177, v235
	v_sub_f32_e32 v178, v178, v235
	v_sub_f32_e32 v179, v179, v235
	v_mfma_f32_16x16x32_bf16 v[40:43], v[172:175], v[140:143], v[40:43]
	v_exp_f32_e32 v176, v176
	v_exp_f32_e32 v177, v177
	v_exp_f32_e32 v178, v178
	v_exp_f32_e32 v179, v179
	v_add_f32_e32 v230, v230, v176
	v_add_f32_e32 v230, v230, v177
	v_add_f32_e32 v230, v230, v178
	v_add_f32_e32 v230, v230, v179
	v_mfma_f32_16x16x32_bf16 v[44:47], v[172:175], v[238:241], v[44:47]
	v_add_f32_e32 v203, v203, v230
	v_cvt_pk_bf16_f32 v152, v152, v153
	v_cvt_pk_bf16_f32 v153, v154, v155
	v_cvt_pk_bf16_f32 v154, v176, v177
	v_cvt_pk_bf16_f32 v155, v178, v179
	s_nop 1
	v_mfma_f32_16x16x32_bf16 v[16:19], v[152:155], v[168:171], v[16:19]
	v_sub_f32_e32 v144, v144, v234
	v_sub_f32_e32 v145, v145, v234
	v_sub_f32_e32 v146, v146, v234
	v_sub_f32_e32 v147, v147, v234
	v_exp_f32_e32 v144, v144
	v_exp_f32_e32 v145, v145
	v_exp_f32_e32 v146, v146
	v_exp_f32_e32 v147, v147
	v_mfma_f32_16x16x32_bf16 v[20:23], v[152:155], v[148:151], v[20:23]
	v_add_f32_e32 v180, v180, v144
	v_add_f32_e32 v180, v180, v145
	v_add_f32_e32 v180, v180, v146
	v_add_f32_e32 v180, v180, v147
	v_sub_f32_e32 v164, v164, v234
	v_sub_f32_e32 v165, v165, v234
	v_sub_f32_e32 v166, v166, v234
	v_sub_f32_e32 v167, v167, v234
	v_mfma_f32_16x16x32_bf16 v[24:27], v[152:155], v[140:143], v[24:27]
	v_exp_f32_e32 v164, v164
	v_exp_f32_e32 v165, v165
	v_exp_f32_e32 v166, v166
	v_exp_f32_e32 v167, v167
	v_add_f32_e32 v180, v180, v164
	v_add_f32_e32 v180, v180, v165
	v_add_f32_e32 v180, v180, v166
	v_add_f32_e32 v180, v180, v167
	v_mfma_f32_16x16x32_bf16 v[28:31], v[152:155], v[238:241], v[28:31]
	v_add_f32_e32 v202, v202, v180
	v_cvt_pk_bf16_f32 v144, v144, v145
	v_cvt_pk_bf16_f32 v145, v146, v147
	v_cvt_pk_bf16_f32 v146, v164, v165
	v_cvt_pk_bf16_f32 v147, v166, v167
	s_nop 1
	v_mfma_f32_16x16x32_bf16 v[0:3], v[144:147], v[168:171], v[0:3]
	v_mfma_f32_16x16x32_bf16 v[4:7], v[144:147], v[148:151], v[4:7]
	v_mfma_f32_16x16x32_bf16 v[8:11], v[144:147], v[140:143], v[8:11]
	v_mfma_f32_16x16x32_bf16 v[12:15], v[144:147], v[238:241], v[12:15]
	s_nop 0
	s_setprio 0
	s_cmp_lg_u32 s11, s25
	v_readlane_b32 s66, v254, 4
	s_cbranch_scc0 .LBB0_220
